# MoBA sub-step loops: permlane32_swap instead of ds_bpermute for the cross-half row max, next sub-step K fragments read during the current softmax; layer-0 gained weight transposes batch 8 row loads
# speedup vs baseline: 1.0042x; 1.0042x over previous
; DI void transpose_item(const float* W, const float* g, int K, int N, bf16_t* WT, float* scr, int item, int lane) {
;     const int nblk = N / 64, kb = item / nblk, nb = item % nblk, k0 = 64 * kb, n0 = 64 * nb;
;     const int lr = lane >> 4, lc = (lane & 15) * 4;
; #pragma unroll 8
;     for (int i = 0; i < 16; ++i) {
;         const int kk = 4 * i + lr; const float gv = g ? g[k0 + kk] : 1.f;
;         const f32x4 v = *(const f32x4*)(W + (size_t)(k0 + kk) * N + n0 + lc);
;         float* d = scr + kk * 65 + lc; d[0] = v.x * gv; d[1] = v.y * gv; d[2] = v.z * gv; d[3] = v.w * gv;
;     }
.LBB0_11:
	v_add_u32_e32 v88, s51, v29
	v_ashrrev_i32_e32 v89, 31, v88
	v_lshl_add_u64 v[90:91], v[88:89], 2, s[30:31]
	global_load_dword v110, v[90:91], off
	global_load_dword v112, v[12:13], off offset:-96
	global_load_dword v114, v[12:13], off offset:-80
	global_load_dword v116, v[12:13], off offset:-64
	global_load_dword v118, v[12:13], off offset:-48
	global_load_dword v120, v[12:13], off offset:-32
	global_load_dword v122, v[12:13], off offset:-16
	global_load_dword v124, v[12:13], off
	v_mad_i64_i32 v[94:95], s[56:57], v88, s54, v[10:11]
	global_load_dwordx4 v[126:129], v[94:95], off
	v_add_u32_e32 v92, 4, v88
	v_mad_i64_i32 v[96:97], s[56:57], v92, s54, v[10:11]
	global_load_dwordx4 v[130:133], v[96:97], off
	v_add_u32_e32 v92, 8, v88
	v_mad_i64_i32 v[98:99], s[56:57], v92, s54, v[10:11]
	global_load_dwordx4 v[134:137], v[98:99], off
	v_add_u32_e32 v92, 12, v88
	v_mad_i64_i32 v[100:101], s[56:57], v92, s54, v[10:11]
	global_load_dwordx4 v[138:141], v[100:101], off
	v_add_u32_e32 v92, 16, v88
	v_mad_i64_i32 v[102:103], s[56:57], v92, s54, v[10:11]
	global_load_dwordx4 v[142:145], v[102:103], off
	v_add_u32_e32 v92, 20, v88
	v_mad_i64_i32 v[104:105], s[56:57], v92, s54, v[10:11]
	global_load_dwordx4 v[146:149], v[104:105], off
	v_add_u32_e32 v92, 24, v88
	v_mad_i64_i32 v[106:107], s[56:57], v92, s54, v[10:11]
	global_load_dwordx4 v[150:153], v[106:107], off
	v_add_u32_e32 v92, 28, v88
	v_mad_i64_i32 v[108:109], s[56:57], v92, s54, v[10:11]
	global_load_dwordx4 v[154:157], v[108:109], off
	v_lshl_add_u64 v[12:13], v[12:13], 0, s[48:49]
	s_waitcnt vmcnt(7)
	v_pk_mul_f32 v[126:127], v[110:111], v[126:127] op_sel_hi:[0,1]
	v_pk_mul_f32 v[128:129], v[110:111], v[128:129] op_sel_hi:[0,1]
	ds_write2_b32 v30, v126, v127 offset1:1
	ds_write2_b32 v30, v128, v129 offset0:2 offset1:3
	s_waitcnt vmcnt(6)
	v_pk_mul_f32 v[130:131], v[112:113], v[130:131] op_sel_hi:[0,1]
	v_pk_mul_f32 v[132:133], v[112:113], v[132:133] op_sel_hi:[0,1]
	v_add_u32_e32 v92, 0x410, v30
	v_add_u32_e32 v93, 0x418, v30
	ds_write2_b32 v92, v130, v131 offset1:1
	ds_write2_b32 v93, v132, v133 offset1:1
	s_waitcnt vmcnt(5)
	v_pk_mul_f32 v[134:135], v[114:115], v[134:135] op_sel_hi:[0,1]
	v_pk_mul_f32 v[136:137], v[114:115], v[136:137] op_sel_hi:[0,1]
	v_add_u32_e32 v92, 0x820, v30
	v_add_u32_e32 v93, 0x828, v30
	ds_write2_b32 v92, v134, v135 offset1:1
	ds_write2_b32 v93, v136, v137 offset1:1
	s_waitcnt vmcnt(4)
	v_pk_mul_f32 v[138:139], v[116:117], v[138:139] op_sel_hi:[0,1]
	v_pk_mul_f32 v[140:141], v[116:117], v[140:141] op_sel_hi:[0,1]
	v_add_u32_e32 v92, 0xc30, v30
	v_add_u32_e32 v93, 0xc38, v30
	ds_write2_b32 v92, v138, v139 offset1:1
	ds_write2_b32 v93, v140, v141 offset1:1
	s_waitcnt vmcnt(3)
	v_pk_mul_f32 v[142:143], v[118:119], v[142:143] op_sel_hi:[0,1]
	v_pk_mul_f32 v[144:145], v[118:119], v[144:145] op_sel_hi:[0,1]
	v_add_u32_e32 v92, 0x1040, v30
	v_add_u32_e32 v93, 0x1048, v30
	ds_write2_b32 v92, v142, v143 offset1:1
	ds_write2_b32 v93, v144, v145 offset1:1
	s_waitcnt vmcnt(2)
	v_pk_mul_f32 v[146:147], v[120:121], v[146:147] op_sel_hi:[0,1]
	v_pk_mul_f32 v[148:149], v[120:121], v[148:149] op_sel_hi:[0,1]
	v_add_u32_e32 v92, 0x1450, v30
	v_add_u32_e32 v93, 0x1458, v30
	ds_write2_b32 v92, v146, v147 offset1:1
	ds_write2_b32 v93, v148, v149 offset1:1
	s_waitcnt vmcnt(1)
	v_pk_mul_f32 v[150:151], v[122:123], v[150:151] op_sel_hi:[0,1]
	v_pk_mul_f32 v[152:153], v[122:123], v[152:153] op_sel_hi:[0,1]
	v_add_u32_e32 v92, 0x1860, v30
	v_add_u32_e32 v93, 0x1868, v30
	ds_write2_b32 v92, v150, v151 offset1:1
	ds_write2_b32 v93, v152, v153 offset1:1
	s_waitcnt vmcnt(0)
	v_pk_mul_f32 v[154:155], v[124:125], v[154:155] op_sel_hi:[0,1]
	v_pk_mul_f32 v[156:157], v[124:125], v[156:157] op_sel_hi:[0,1]
	v_add_u32_e32 v92, 0x1c70, v30
	v_add_u32_e32 v93, 0x1c78, v30
	ds_write2_b32 v92, v154, v155 offset1:1
	ds_write2_b32 v93, v156, v157 offset1:1
	v_add_u32_e32 v30, 0x2080, v30
	s_add_i32 s51, s51, 32
	s_cmp_lg_u32 s51, 64
	s_cbranch_scc1 .LBB0_11
	s_branch .LBB0_8

; DI void transpose_item(const float* W, const float* g, int K, int N, bf16_t* WT, float* scr, int item, int lane) {
;     const int nblk = N / 64, kb = item / nblk, nb = item % nblk, k0 = 64 * kb, n0 = 64 * nb;
;     const int lr = lane >> 4, lc = (lane & 15) * 4;
; #pragma unroll 8
;     for (int i = 0; i < 16; ++i) {
;         const int kk = 4 * i + lr; const float gv = g ? g[k0 + kk] : 1.f;
;         const f32x4 v = *(const f32x4*)(W + (size_t)(k0 + kk) * N + n0 + lc);
;         float* d = scr + kk * 65 + lc; d[0] = v.x * gv; d[1] = v.y * gv; d[2] = v.z * gv; d[3] = v.w * gv;
;     }
.LBB0_37:
	v_add_u32_e32 v88, s53, v30
	v_ashrrev_i32_e32 v89, 31, v88
	v_lshl_add_u64 v[90:91], v[88:89], 2, s[12:13]
	global_load_dword v110, v[90:91], off
	global_load_dword v112, v[14:15], off offset:-96
	global_load_dword v114, v[14:15], off offset:-80
	global_load_dword v116, v[14:15], off offset:-64
	global_load_dword v118, v[14:15], off offset:-48
	global_load_dword v120, v[14:15], off offset:-32
	global_load_dword v122, v[14:15], off offset:-16
	global_load_dword v124, v[14:15], off
	v_lshlrev_b64 v[94:95], 14, v[88:89]
	v_lshl_add_u64 v[94:95], v[12:13], 0, v[94:95]
	global_load_dwordx4 v[126:129], v[94:95], off
	v_add_u32_e32 v92, 4, v88
	v_ashrrev_i32_e32 v93, 31, v92
	v_lshlrev_b64 v[96:97], 14, v[92:93]
	v_lshl_add_u64 v[96:97], v[12:13], 0, v[96:97]
	global_load_dwordx4 v[130:133], v[96:97], off
	v_add_u32_e32 v92, 8, v88
	v_ashrrev_i32_e32 v93, 31, v92
	v_lshlrev_b64 v[98:99], 14, v[92:93]
	v_lshl_add_u64 v[98:99], v[12:13], 0, v[98:99]
	global_load_dwordx4 v[134:137], v[98:99], off
	v_add_u32_e32 v92, 12, v88
	v_ashrrev_i32_e32 v93, 31, v92
	v_lshlrev_b64 v[100:101], 14, v[92:93]
	v_lshl_add_u64 v[100:101], v[12:13], 0, v[100:101]
	global_load_dwordx4 v[138:141], v[100:101], off
	v_add_u32_e32 v92, 16, v88
	v_ashrrev_i32_e32 v93, 31, v92
	v_lshlrev_b64 v[102:103], 14, v[92:93]
	v_lshl_add_u64 v[102:103], v[12:13], 0, v[102:103]
	global_load_dwordx4 v[142:145], v[102:103], off
	v_add_u32_e32 v92, 20, v88
	v_ashrrev_i32_e32 v93, 31, v92
	v_lshlrev_b64 v[104:105], 14, v[92:93]
	v_lshl_add_u64 v[104:105], v[12:13], 0, v[104:105]
	global_load_dwordx4 v[146:149], v[104:105], off
	v_add_u32_e32 v92, 24, v88
	v_ashrrev_i32_e32 v93, 31, v92
	v_lshlrev_b64 v[106:107], 14, v[92:93]
	v_lshl_add_u64 v[106:107], v[12:13], 0, v[106:107]
	global_load_dwordx4 v[150:153], v[106:107], off
	v_add_u32_e32 v92, 28, v88
	v_ashrrev_i32_e32 v93, 31, v92
	v_lshlrev_b64 v[108:109], 14, v[92:93]
	v_lshl_add_u64 v[108:109], v[12:13], 0, v[108:109]
	global_load_dwordx4 v[154:157], v[108:109], off
	v_lshl_add_u64 v[14:15], v[14:15], 0, s[50:51]
	s_waitcnt vmcnt(7)
	v_pk_mul_f32 v[126:127], v[110:111], v[126:127] op_sel_hi:[0,1]
	v_pk_mul_f32 v[128:129], v[110:111], v[128:129] op_sel_hi:[0,1]
	ds_write2_b32 v31, v126, v127 offset1:1
	ds_write2_b32 v31, v128, v129 offset0:2 offset1:3
	s_waitcnt vmcnt(6)
	v_pk_mul_f32 v[130:131], v[112:113], v[130:131] op_sel_hi:[0,1]
	v_pk_mul_f32 v[132:133], v[112:113], v[132:133] op_sel_hi:[0,1]
	v_add_u32_e32 v92, 0x410, v31
	v_add_u32_e32 v93, 0x418, v31
	ds_write2_b32 v92, v130, v131 offset1:1
	ds_write2_b32 v93, v132, v133 offset1:1
	s_waitcnt vmcnt(5)
	v_pk_mul_f32 v[134:135], v[114:115], v[134:135] op_sel_hi:[0,1]
	v_pk_mul_f32 v[136:137], v[114:115], v[136:137] op_sel_hi:[0,1]
	v_add_u32_e32 v92, 0x820, v31
	v_add_u32_e32 v93, 0x828, v31
	ds_write2_b32 v92, v134, v135 offset1:1
	ds_write2_b32 v93, v136, v137 offset1:1
	s_waitcnt vmcnt(4)
	v_pk_mul_f32 v[138:139], v[116:117], v[138:139] op_sel_hi:[0,1]
	v_pk_mul_f32 v[140:141], v[116:117], v[140:141] op_sel_hi:[0,1]
	v_add_u32_e32 v92, 0xc30, v31
	v_add_u32_e32 v93, 0xc38, v31
	ds_write2_b32 v92, v138, v139 offset1:1
	ds_write2_b32 v93, v140, v141 offset1:1
	s_waitcnt vmcnt(3)
	v_pk_mul_f32 v[142:143], v[118:119], v[142:143] op_sel_hi:[0,1]
	v_pk_mul_f32 v[144:145], v[118:119], v[144:145] op_sel_hi:[0,1]
	v_add_u32_e32 v92, 0x1040, v31
	v_add_u32_e32 v93, 0x1048, v31
	ds_write2_b32 v92, v142, v143 offset1:1
	ds_write2_b32 v93, v144, v145 offset1:1
	s_waitcnt vmcnt(2)
	v_pk_mul_f32 v[146:147], v[120:121], v[146:147] op_sel_hi:[0,1]
	v_pk_mul_f32 v[148:149], v[120:121], v[148:149] op_sel_hi:[0,1]
	v_add_u32_e32 v92, 0x1450, v31
	v_add_u32_e32 v93, 0x1458, v31
	ds_write2_b32 v92, v146, v147 offset1:1
	ds_write2_b32 v93, v148, v149 offset1:1
	s_waitcnt vmcnt(1)
	v_pk_mul_f32 v[150:151], v[122:123], v[150:151] op_sel_hi:[0,1]
	v_pk_mul_f32 v[152:153], v[122:123], v[152:153] op_sel_hi:[0,1]
	v_add_u32_e32 v92, 0x1860, v31
	v_add_u32_e32 v93, 0x1868, v31
	ds_write2_b32 v92, v150, v151 offset1:1
	ds_write2_b32 v93, v152, v153 offset1:1
	s_waitcnt vmcnt(0)
	v_pk_mul_f32 v[154:155], v[124:125], v[154:155] op_sel_hi:[0,1]
	v_pk_mul_f32 v[156:157], v[124:125], v[156:157] op_sel_hi:[0,1]
	v_add_u32_e32 v92, 0x1c70, v31
	v_add_u32_e32 v93, 0x1c78, v31
	ds_write2_b32 v92, v154, v155 offset1:1
	ds_write2_b32 v93, v156, v157 offset1:1
	v_add_u32_e32 v31, 0x2080, v31
	s_add_i32 s53, s53, 32
	s_cmp_lg_u32 s53, 64
	s_cbranch_scc1 .LBB0_37
	s_branch .LBB0_34

; DI void transpose_item(const float* W, const float* g, int K, int N, bf16_t* WT, float* scr, int item, int lane) {
;     const int nblk = N / 64, kb = item / nblk, nb = item % nblk, k0 = 64 * kb, n0 = 64 * nb;
;     const int lr = lane >> 4, lc = (lane & 15) * 4;
; #pragma unroll 8
;     for (int i = 0; i < 16; ++i) {
;         const int kk = 4 * i + lr; const float gv = g ? g[k0 + kk] : 1.f;
;         const f32x4 v = *(const f32x4*)(W + (size_t)(k0 + kk) * N + n0 + lc);
;         float* d = scr + kk * 65 + lc; d[0] = v.x * gv; d[1] = v.y * gv; d[2] = v.z * gv; d[3] = v.w * gv;
;     }
.LBB0_62:
	v_add_u32_e32 v88, s53, v29
	v_ashrrev_i32_e32 v89, 31, v88
	v_lshl_add_u64 v[90:91], v[88:89], 2, s[18:19]
	global_load_dword v110, v[90:91], off
	global_load_dword v112, v[12:13], off offset:-96
	global_load_dword v114, v[12:13], off offset:-80
	global_load_dword v116, v[12:13], off offset:-64
	global_load_dword v118, v[12:13], off offset:-48
	global_load_dword v120, v[12:13], off offset:-32
	global_load_dword v122, v[12:13], off offset:-16
	global_load_dword v124, v[12:13], off
	v_lshlrev_b64 v[94:95], 12, v[88:89]
	v_lshl_add_u64 v[94:95], v[10:11], 0, v[94:95]
	global_load_dwordx4 v[126:129], v[94:95], off
	v_add_u32_e32 v92, 4, v88
	v_ashrrev_i32_e32 v93, 31, v92
	v_lshlrev_b64 v[96:97], 12, v[92:93]
	v_lshl_add_u64 v[96:97], v[10:11], 0, v[96:97]
	global_load_dwordx4 v[130:133], v[96:97], off
	v_add_u32_e32 v92, 8, v88
	v_ashrrev_i32_e32 v93, 31, v92
	v_lshlrev_b64 v[98:99], 12, v[92:93]
	v_lshl_add_u64 v[98:99], v[10:11], 0, v[98:99]
	global_load_dwordx4 v[134:137], v[98:99], off
	v_add_u32_e32 v92, 12, v88
	v_ashrrev_i32_e32 v93, 31, v92
	v_lshlrev_b64 v[100:101], 12, v[92:93]
	v_lshl_add_u64 v[100:101], v[10:11], 0, v[100:101]
	global_load_dwordx4 v[138:141], v[100:101], off
	v_add_u32_e32 v92, 16, v88
	v_ashrrev_i32_e32 v93, 31, v92
	v_lshlrev_b64 v[102:103], 12, v[92:93]
	v_lshl_add_u64 v[102:103], v[10:11], 0, v[102:103]
	global_load_dwordx4 v[142:145], v[102:103], off
	v_add_u32_e32 v92, 20, v88
	v_ashrrev_i32_e32 v93, 31, v92
	v_lshlrev_b64 v[104:105], 12, v[92:93]
	v_lshl_add_u64 v[104:105], v[10:11], 0, v[104:105]
	global_load_dwordx4 v[146:149], v[104:105], off
	v_add_u32_e32 v92, 24, v88
	v_ashrrev_i32_e32 v93, 31, v92
	v_lshlrev_b64 v[106:107], 12, v[92:93]
	v_lshl_add_u64 v[106:107], v[10:11], 0, v[106:107]
	global_load_dwordx4 v[150:153], v[106:107], off
	v_add_u32_e32 v92, 28, v88
	v_ashrrev_i32_e32 v93, 31, v92
	v_lshlrev_b64 v[108:109], 12, v[92:93]
	v_lshl_add_u64 v[108:109], v[10:11], 0, v[108:109]
	global_load_dwordx4 v[154:157], v[108:109], off
	v_lshl_add_u64 v[12:13], v[12:13], 0, s[50:51]
	s_waitcnt vmcnt(7)
	v_pk_mul_f32 v[126:127], v[110:111], v[126:127] op_sel_hi:[0,1]
	v_pk_mul_f32 v[128:129], v[110:111], v[128:129] op_sel_hi:[0,1]
	ds_write2_b32 v30, v126, v127 offset1:1
	ds_write2_b32 v30, v128, v129 offset0:2 offset1:3
	s_waitcnt vmcnt(6)
	v_pk_mul_f32 v[130:131], v[112:113], v[130:131] op_sel_hi:[0,1]
	v_pk_mul_f32 v[132:133], v[112:113], v[132:133] op_sel_hi:[0,1]
	v_add_u32_e32 v92, 0x410, v30
	v_add_u32_e32 v93, 0x418, v30
	ds_write2_b32 v92, v130, v131 offset1:1
	ds_write2_b32 v93, v132, v133 offset1:1
	s_waitcnt vmcnt(5)
	v_pk_mul_f32 v[134:135], v[114:115], v[134:135] op_sel_hi:[0,1]
	v_pk_mul_f32 v[136:137], v[114:115], v[136:137] op_sel_hi:[0,1]
	v_add_u32_e32 v92, 0x820, v30
	v_add_u32_e32 v93, 0x828, v30
	ds_write2_b32 v92, v134, v135 offset1:1
	ds_write2_b32 v93, v136, v137 offset1:1
	s_waitcnt vmcnt(4)
	v_pk_mul_f32 v[138:139], v[116:117], v[138:139] op_sel_hi:[0,1]
	v_pk_mul_f32 v[140:141], v[116:117], v[140:141] op_sel_hi:[0,1]
	v_add_u32_e32 v92, 0xc30, v30
	v_add_u32_e32 v93, 0xc38, v30
	ds_write2_b32 v92, v138, v139 offset1:1
	ds_write2_b32 v93, v140, v141 offset1:1
	s_waitcnt vmcnt(3)
	v_pk_mul_f32 v[142:143], v[118:119], v[142:143] op_sel_hi:[0,1]
	v_pk_mul_f32 v[144:145], v[118:119], v[144:145] op_sel_hi:[0,1]
	v_add_u32_e32 v92, 0x1040, v30
	v_add_u32_e32 v93, 0x1048, v30
	ds_write2_b32 v92, v142, v143 offset1:1
	ds_write2_b32 v93, v144, v145 offset1:1
	s_waitcnt vmcnt(2)
	v_pk_mul_f32 v[146:147], v[120:121], v[146:147] op_sel_hi:[0,1]
	v_pk_mul_f32 v[148:149], v[120:121], v[148:149] op_sel_hi:[0,1]
	v_add_u32_e32 v92, 0x1450, v30
	v_add_u32_e32 v93, 0x1458, v30
	ds_write2_b32 v92, v146, v147 offset1:1
	ds_write2_b32 v93, v148, v149 offset1:1
	s_waitcnt vmcnt(1)
	v_pk_mul_f32 v[150:151], v[122:123], v[150:151] op_sel_hi:[0,1]
	v_pk_mul_f32 v[152:153], v[122:123], v[152:153] op_sel_hi:[0,1]
	v_add_u32_e32 v92, 0x1860, v30
	v_add_u32_e32 v93, 0x1868, v30
	ds_write2_b32 v92, v150, v151 offset1:1
	ds_write2_b32 v93, v152, v153 offset1:1
	s_waitcnt vmcnt(0)
	v_pk_mul_f32 v[154:155], v[124:125], v[154:155] op_sel_hi:[0,1]
	v_pk_mul_f32 v[156:157], v[124:125], v[156:157] op_sel_hi:[0,1]
	v_add_u32_e32 v92, 0x1c70, v30
	v_add_u32_e32 v93, 0x1c78, v30
	ds_write2_b32 v92, v154, v155 offset1:1
	ds_write2_b32 v93, v156, v157 offset1:1
	v_add_u32_e32 v30, 0x2080, v30
	s_add_i32 s53, s53, 32
	s_cmp_lg_u32 s53, 64
	s_cbranch_scc1 .LBB0_62
	s_branch .LBB0_59

; #define MS_QLOAD(TL) do { const int e_ = (TL) * 32 + r32; validn = e_ < cnt; entn = list[validn ? e_ : 0]; const int s_ = entn >> 2; \
;         _Pragma("unroll") for (int c = 0; c < 4; ++c) qn[c] = *(const bf16x8*)(QKV + ((size_t)b * SEQ + s_) * QKVW + h * 64 + 16 * c + 8 * hi); } while (0)
; DI void moba_tile(const unsigned char* lds, LAS unsigned char* lds3, const bf16x8 (&qf)[4], int nsub, int diag_sub, int lane, f32x16 (&o)[2], float& m, float& l) {
;     ...
;         for (int c = 0; c < 4; ++c) kf[c] = *(const bf16x8*)(lds + MB_K + (32 * kk + r32) * 144 + (16 * c + 8 * hi) * 2);
; DI void phase_moba_sel(const Args& A, unsigned char* lds, LAS unsigned char* lds3, int tid, int wid, int lane) {
;     ...
;         if (wid < ntile) MS_QLOAD(wid);
;         for (int tl = wid; tl < ntile; tl += NWAVES) {
;             const bool valid = validn; const int ent = entn;
;             const int s = ent >> 2, slot = ent & 3;
;             bf16x8 qf[4];
; #pragma unroll
;             for (int c = 0; c < 4; ++c) qf[c] = qn[c];
;             { const int tn = (tl + NWAVES < ntile) ? tl + NWAVES : tl; MS_QLOAD(tn); }
;             f32x16 o[2];
; #pragma unroll
;             for (int i = 0; i < 16; ++i) { o[0][i] = 0.f; o[1][i] = 0.f; }
;             float m = -INFINITY, l = 0.f;
;             moba_tile(lds, lds3, qf, 8, -1, lane, o, m, l);
.LBB0_1307:
	s_mov_b64 s[28:29], s[8:9]
	s_mov_b32 s8, s34
	s_add_i32 s34, s34, 8
	s_waitcnt lgkmcnt(0)
	v_mov_b32_e32 v0, s8
	v_mov_b32_e32 v2, s34
	v_cmp_lt_i32_e32 vcc, s34, v107
	v_mov_b32_e32 v146, v117
	s_waitcnt vmcnt(0)
	v_mov_b64_e32 v[68:69], v[64:65]
	v_cndmask_b32_e32 v0, v0, v2, vcc
	v_lshl_or_b32 v0, v0, 5, v126
	v_cmp_lt_i32_e64 s[8:9], v0, v103
	v_mov_b64_e32 v[72:73], v[60:61]
	v_mov_b64_e32 v[76:77], v[56:57]
	v_cndmask_b32_e64 v0, 0, v0, s[8:9]
	v_lshl_add_u32 v0, v0, 1, v142
	ds_read_u16 v117, v0
	v_mov_b64_e32 v[80:81], v[52:53]
	v_mov_b64_e32 v[66:67], v[62:63]
	v_mov_b64_e32 v[70:71], v[58:59]
	v_mov_b64_e32 v[74:75], v[54:55]
	s_waitcnt lgkmcnt(0)
	v_lshrrev_b32_e32 v0, 2, v117
	v_or_b32_e32 v0, v0, v120
	v_mul_u32_u24_e32 v0, 0xc00, v0
	v_lshlrev_b32_e32 v0, 1, v0
	v_lshl_add_u64 v[2:3], v[122:123], 0, v[0:1]
	v_mov_b64_e32 v[78:79], v[50:51]
	global_load_dwordx4 v[50:53], v[2:3], off
	global_load_dwordx4 v[54:57], v[2:3], off offset:32
	global_load_dwordx4 v[58:61], v[2:3], off offset:64
	global_load_dwordx4 v[62:65], v[2:3], off offset:96
	v_mov_b32_e32 v2, v1
	v_mov_b32_e32 v3, v1
	v_mov_b32_e32 v4, v1
	v_mov_b32_e32 v5, v1
	v_mov_b32_e32 v6, v1
	v_mov_b32_e32 v7, v1
	v_mov_b32_e32 v8, v1
	v_mov_b32_e32 v9, v1
	v_mov_b32_e32 v10, v1
	v_mov_b32_e32 v11, v1
	v_mov_b32_e32 v12, v1
	v_mov_b32_e32 v13, v1
	v_mov_b32_e32 v14, v1
	v_mov_b32_e32 v15, v1
	v_mov_b32_e32 v16, v1
	v_mov_b32_e32 v17, v1
	v_mov_b32_e32 v18, v1
	v_mov_b32_e32 v19, v1
	v_mov_b32_e32 v20, v1
	v_mov_b32_e32 v21, v1
	v_mov_b32_e32 v22, v1
	v_mov_b32_e32 v23, v1
	v_mov_b32_e32 v24, v1
	v_mov_b32_e32 v25, v1
	v_mov_b32_e32 v26, v1
	v_mov_b32_e32 v27, v1
	v_mov_b32_e32 v28, v1
	v_mov_b32_e32 v29, v1
	v_mov_b32_e32 v30, v1
	v_mov_b32_e32 v31, v1
	v_cmp_ge_i32_e32 vcc, s34, v107
	v_mov_b32_e32 v0, v1
	v_mov_b64_e32 v[32:33], v[30:31]
	s_mov_b32 s30, 8
	s_or_b64 s[26:27], vcc, s[26:27]
	v_mov_b32_e32 v125, 0
	v_mov_b32_e32 v124, 0xff800000
	v_mov_b32_e32 v147, v133
	v_mov_b32_e32 v148, v132
	v_mov_b64_e32 v[30:31], v[28:29]
	v_mov_b64_e32 v[28:29], v[26:27]
	v_mov_b64_e32 v[26:27], v[24:25]
	v_mov_b64_e32 v[24:25], v[22:23]
	v_mov_b64_e32 v[22:23], v[20:21]
	v_mov_b64_e32 v[20:21], v[18:19]
	v_mov_b64_e32 v[18:19], v[16:17]
	v_mov_b64_e32 v[16:17], v[14:15]
	v_mov_b64_e32 v[14:15], v[12:13]
	v_mov_b64_e32 v[12:13], v[10:11]
	v_mov_b64_e32 v[10:11], v[8:9]
	v_mov_b64_e32 v[8:9], v[6:7]
	v_mov_b64_e32 v[6:7], v[4:5]
	v_mov_b64_e32 v[4:5], v[2:3]
	v_mov_b64_e32 v[2:3], v[0:1]
	v_add_u32_e32 v0, v147, v129
	ds_read_b128 v[192:195], v0
	ds_read_b128 v[196:199], v0 offset:32
	ds_read_b128 v[200:203], v0 offset:64
	ds_read_b128 v[204:207], v0 offset:96
	s_branch .LBB0_1309

; #define LAS __attribute__((address_space(3)))
; DI float xhalf(float v) { return __shfl_xor(v, 32); }
; DI f32x16 mfma32(bf16x8 a, bf16x8 b, f32x16 c) { return __builtin_amdgcn_mfma_f32_32x32x16_bf16(a, b, c, 0, 0, 0); }
; DI bf16x8 vfrag(LAS unsigned char* p) { const s16x4 lo = tr_read(p), hi = tr_read(p + 512); return __builtin_shufflevector(lo, hi, 0, 1, 2, 3, 4, 5, 6, 7); }
; DI float fexp2(float x) { return __builtin_amdgcn_exp2f(x); }
; DI void moba_tile(const unsigned char* lds, LAS unsigned char* lds3, const bf16x8 (&qf)[4], int nsub, int diag_sub, int lane, f32x16 (&o)[2], float& m, float& l) {
;     ...
;     for (int kk = 0; kk < nsub; ++kk) {
;         bf16x8 kf[4], vf[4];
; #pragma unroll
;         for (int c = 0; c < 4; ++c) kf[c] = *(const bf16x8*)(lds + MB_K + (32 * kk + r32) * 144 + (16 * c + 8 * hi) * 2);
; #pragma unroll
;         for (int dt = 0; dt < 2; ++dt) { LAS unsigned char* vb = lds3 + MB_V + dt * 16384 + (32 * kk) * 64 + vlane; vf[2 * dt] = vfrag(vb); vf[2 * dt + 1] = vfrag(vb + 1024); }
;         f32x16 s;
; #pragma unroll
;         for (int i = 0; i < 16; ++i) s[i] = 0.f;
; #pragma unroll
;         for (int c = 0; c < 4; ++c) s = mfma32(kf[c], qf[c], s);
;         if (kk == diag_sub) {
;             const int dq = r32 - 4 * hi;
; #pragma unroll
;             for (int i = 0; i < 16; ++i) s[i] = (((i & 3) + 8 * (i >> 2)) > dq) ? -INFINITY : s[i];
;         }
;         float mx = fmaxf(fmaxf(s[0], s[1]), s[2]);
; #pragma unroll
;         for (int i = 3; i < 15; i += 2) mx = fmaxf(fmaxf(mx, s[i]), s[i + 1]);
;         mx = fmaxf(mx, s[15]);
;         mx = fmaxf(mx, xhalf(mx)) * SCL2;
;         const bool trig = mx > m + 8.f;
;         if (__any(trig)) {
;             const float mn = trig ? mx : m, al = fexp2(m - mn); l *= al; m = mn;
; #pragma unroll
;             for (int dt = 0; dt < 2; ++dt)
; #pragma unroll
;                 for (int i = 0; i < 16; ++i) o[dt][i] *= al;
;         }
.LBB0_1309:
	s_waitcnt lgkmcnt(0)
	v_mfma_f32_32x32x16_bf16 v[34:49], v[192:195], v[78:81], 0
	v_mfma_f32_32x32x16_bf16 v[34:49], v[196:199], v[74:77], v[34:49]
	v_mfma_f32_32x32x16_bf16 v[34:49], v[200:203], v[70:73], v[34:49]
	v_mfma_f32_32x32x16_bf16 v[34:49], v[204:207], v[66:69], v[34:49]
	v_add_u32_e32 v0, v147, v129
	ds_read_b128 v[192:195], v0 offset:4608
	ds_read_b128 v[196:199], v0 offset:4640
	ds_read_b128 v[200:203], v0 offset:4672
	ds_read_b128 v[204:207], v0 offset:4704
	v_add_u32_e32 v0, v148, v129
	ds_read_b64_tr_b16 v[94:95], v0 offset:36864
	ds_read_b64_tr_b16 v[96:97], v0 offset:37376
	ds_read_b64_tr_b16 v[90:91], v0 offset:37888
	ds_read_b64_tr_b16 v[92:93], v0 offset:38400
	s_nop 2
	v_max_f32_e32 v82, v35, v35
	v_max_f32_e32 v83, v34, v34
	v_max_f32_e32 v82, v83, v82
	v_max3_f32 v82, v82, v36, v37
	v_max3_f32 v82, v82, v38, v39
	v_max3_f32 v82, v82, v40, v41
	v_max3_f32 v82, v82, v42, v43
	v_max3_f32 v82, v82, v44, v45
	v_max3_f32 v82, v82, v46, v47
	v_max3_f32 v149, v82, v48, v49
	v_mov_b32_e32 v150, v149
	ds_read_b64_tr_b16 v[86:87], v0 offset:53248
	ds_read_b64_tr_b16 v[88:89], v0 offset:53760
	ds_read_b64_tr_b16 v[82:83], v0 offset:54272
	ds_read_b64_tr_b16 v[84:85], v0 offset:54784
	s_waitcnt lgkmcnt(4)
	v_permlane32_swap_b32_e32 v149, v150
	v_max_f32_e32 v0, v149, v150
	v_mul_f32_e32 v0, 0x3e38aa3b, v0
	v_add_f32_e32 v149, 0x41000000, v124
	v_cmp_gt_f32_e32 vcc, v0, v149
	s_cbranch_vccz .LBB0_1308
	s_nop 0
	v_cndmask_b32_e32 v149, v124, v0, vcc
	v_sub_f32_e32 v0, v124, v149
	v_exp_f32_e32 v0, v0
	v_mov_b32_e32 v124, v149
	v_mul_f32_e32 v125, v125, v0
	v_pk_mul_f32 v[32:33], v[32:33], v[0:1] op_sel_hi:[1,0]
	v_pk_mul_f32 v[30:31], v[30:31], v[0:1] op_sel_hi:[1,0]
	v_pk_mul_f32 v[28:29], v[28:29], v[0:1] op_sel_hi:[1,0]
	v_pk_mul_f32 v[26:27], v[26:27], v[0:1] op_sel_hi:[1,0]
	v_pk_mul_f32 v[24:25], v[24:25], v[0:1] op_sel_hi:[1,0]
	v_pk_mul_f32 v[22:23], v[22:23], v[0:1] op_sel_hi:[1,0]
	v_pk_mul_f32 v[20:21], v[20:21], v[0:1] op_sel_hi:[1,0]
	v_pk_mul_f32 v[18:19], v[18:19], v[0:1] op_sel_hi:[1,0]
	v_pk_mul_f32 v[16:17], v[16:17], v[0:1] op_sel_hi:[1,0]
	v_pk_mul_f32 v[14:15], v[14:15], v[0:1] op_sel_hi:[1,0]
	v_pk_mul_f32 v[12:13], v[12:13], v[0:1] op_sel_hi:[1,0]
	v_pk_mul_f32 v[10:11], v[10:11], v[0:1] op_sel_hi:[1,0]
	v_pk_mul_f32 v[8:9], v[8:9], v[0:1] op_sel_hi:[1,0]
	v_pk_mul_f32 v[6:7], v[6:7], v[0:1] op_sel_hi:[1,0]
	v_pk_mul_f32 v[4:5], v[4:5], v[0:1] op_sel_hi:[1,0]
	v_pk_mul_f32 v[2:3], v[2:3], v[0:1] op_sel_hi:[1,0]
	s_branch .LBB0_1308

; DI void moba_tile(const unsigned char* lds, LAS unsigned char* lds3, const bf16x8 (&qf)[4], int nsub, int diag_sub, int lane, f32x16 (&o)[2], float& m, float& l) {
;     ...
;         for (int c = 0; c < 4; ++c) kf[c] = *(const bf16x8*)(lds + MB_K + (32 * kk + r32) * 144 + (16 * c + 8 * hi) * 2);
; DI void phase_moba_own(const Args& A, unsigned char* lds, LAS unsigned char* lds3, int tid, int wid, int lane) {
;     ...
;             const int tile = pass == 0 ? g4 : 7 - g4;
;             const int s = i * 256 + tile * 32 + r32;
;             bf16x8 qf[4];
; #pragma unroll
;             for (int c = 0; c < 4; ++c) qf[c] = *(const bf16x8*)(QKV + ((size_t)b * SEQ + s) * QKVW + h * 64 + 16 * c + 8 * hi);
;             f32x16 o[2];
; #pragma unroll
;             for (int k = 0; k < 16; ++k) { o[0][k] = 0.f; o[1][k] = 0.f; }
;             float m = -INFINITY, l = 0.f;
;             const unsigned w = SEL[(size_t)bh * SEQ + s];
;             const size_t pe0 = ((size_t)bh * SEQ + s) * 3;
;             float pm[3], pl[3]; u32x2 pw[3][8];
; #pragma unroll
;             for (int slot = 0; slot < 3; ++slot) {
;                 { typedef float f32x2_t __attribute__((ext_vector_type(2))); const f32x2_t ml = *(const f32x2_t*)(PML + (pe0 + slot) * 2); pm[slot] = ml.x; pl[slot] = ml.y; }
; #pragma unroll
;                 for (int dt = 0; dt < 2; ++dt)
; #pragma unroll
;                     for (int gp = 0; gp < 2; ++gp) { const u32x4 q4 = *(const u32x4*)(PO + (pe0 + slot) * 64 + hi * 32 + dt * 16 + gp * 8); pw[slot][dt * 4 + 2 * gp] = (u32x2){q4.x, q4.y}; pw[slot][dt * 4 + 2 * gp + 1] = (u32x2){q4.z, q4.w}; }
;             }
;             moba_tile(ldsg, lds3g, qf, tile + 1, tile, lane, o, m, l);
.LBB0_1375:
	s_and_b64 s[60:61], s[62:63], exec
	s_cselect_b32 s50, s66, s72
	s_lshl_b32 s80, s50, 5
	v_or_b32_e32 v151, s80, v169
	v_or_b32_e32 v0, s54, v151
	v_mad_u64_u32 v[2:3], s[60:61], v0, s74, v[154:155]
	v_or_b32_e32 v4, s56, v151
	v_mad_i32_i24 v3, s55, v166, v3
	v_mad_u64_u32 v[8:9], s[60:61], v4, 24, s[48:49]
	global_load_dwordx4 v[110:113], v[2:3], off offset:32
	global_load_dwordx4 v[106:109], v[2:3], off offset:64
	global_load_dwordx4 v[102:105], v[2:3], off offset:96
	v_mad_i32_i24 v9, s57, 24, v9
	global_load_dwordx4 v[114:117], v[2:3], off
	global_load_dwordx2 v[156:157], v[8:9], off offset:16
	v_mad_u64_u32 v[2:3], s[60:61], v4, s76, v[136:137]
	v_mov_b32_e32 v5, s57
	v_mad_i32_i24 v3, s57, v167, v3
	v_lshl_add_u64 v[6:7], v[4:5], 2, s[46:47]
	global_load_dwordx4 v[90:93], v[2:3], off offset:32
	global_load_dwordx4 v[94:97], v[2:3], off offset:16
	global_load_dword v153, v[6:7], off
	global_load_dwordx4 v[98:101], v[2:3], off
	global_load_dwordx4 v[70:73], v[2:3], off offset:160
	global_load_dwordx4 v[74:77], v[2:3], off offset:144
	global_load_dwordx4 v[86:89], v[2:3], off offset:48
	global_load_dwordx4 v[78:81], v[2:3], off offset:128
	global_load_dwordx4 v[82:85], v[8:9], off
	global_load_dwordx4 v[50:53], v[2:3], off offset:304
	global_load_dwordx4 v[54:57], v[2:3], off offset:288
	global_load_dwordx4 v[58:61], v[2:3], off offset:272
	global_load_dwordx4 v[66:69], v[2:3], off offset:176
	global_load_dwordx4 v[62:65], v[2:3], off offset:256
	v_mov_b32_e32 v0, v1
	v_mov_b32_e32 v2, v1
	v_mov_b32_e32 v3, v1
	v_mov_b32_e32 v4, v1
	v_mov_b32_e32 v5, v1
	v_mov_b32_e32 v6, v1
	v_mov_b32_e32 v7, v1
	v_mov_b32_e32 v8, v1
	v_mov_b32_e32 v9, v1
	v_mov_b32_e32 v10, v1
	v_mov_b32_e32 v11, v1
	v_mov_b32_e32 v12, v1
	v_mov_b32_e32 v13, v1
	v_mov_b32_e32 v14, v1
	v_mov_b32_e32 v15, v1
	v_mov_b32_e32 v16, v1
	v_mov_b32_e32 v17, v1
	v_mov_b32_e32 v18, v1
	v_mov_b32_e32 v19, v1
	v_mov_b32_e32 v20, v1
	v_mov_b32_e32 v21, v1
	v_mov_b32_e32 v22, v1
	v_mov_b32_e32 v23, v1
	v_mov_b32_e32 v24, v1
	v_mov_b32_e32 v25, v1
	v_mov_b32_e32 v26, v1
	v_mov_b32_e32 v27, v1
	v_mov_b32_e32 v28, v1
	v_mov_b32_e32 v29, v1
	v_mov_b32_e32 v30, v1
	v_mov_b32_e32 v31, v1
	s_cmp_lg_u32 s50, 0
	s_cbranch_scc0 .LBB0_1380
	v_mov_b64_e32 v[32:33], v[30:31]
	v_mov_b32_e32 v171, 0
	v_mov_b32_e32 v170, 0xff800000
	v_mov_b32_e32 v172, v163
	v_mov_b32_e32 v173, v162
	s_mov_b32 s60, s50
	v_mov_b64_e32 v[30:31], v[28:29]
	v_mov_b64_e32 v[28:29], v[26:27]
	v_mov_b64_e32 v[26:27], v[24:25]
	v_mov_b64_e32 v[24:25], v[22:23]
	v_mov_b64_e32 v[22:23], v[20:21]
	v_mov_b64_e32 v[20:21], v[18:19]
	v_mov_b64_e32 v[18:19], v[16:17]
	v_mov_b64_e32 v[16:17], v[14:15]
	v_mov_b64_e32 v[14:15], v[12:13]
	v_mov_b64_e32 v[12:13], v[10:11]
	v_mov_b64_e32 v[10:11], v[8:9]
	v_mov_b64_e32 v[8:9], v[6:7]
	v_mov_b64_e32 v[6:7], v[4:5]
	v_mov_b64_e32 v[4:5], v[2:3]
	v_mov_b64_e32 v[2:3], v[0:1]
	v_add_u32_e32 v0, s67, v172
	ds_read_b128 v[192:195], v0
	ds_read_b128 v[196:199], v0 offset:32
	ds_read_b128 v[200:203], v0 offset:64
	ds_read_b128 v[204:207], v0 offset:96
	s_branch .LBB0_1378

; #define LAS __attribute__((address_space(3)))
; DI float xhalf(float v) { return __shfl_xor(v, 32); }
; DI f32x16 mfma32(bf16x8 a, bf16x8 b, f32x16 c) { return __builtin_amdgcn_mfma_f32_32x32x16_bf16(a, b, c, 0, 0, 0); }
; DI bf16x8 vfrag(LAS unsigned char* p) { const s16x4 lo = tr_read(p), hi = tr_read(p + 512); return __builtin_shufflevector(lo, hi, 0, 1, 2, 3, 4, 5, 6, 7); }
; DI float fexp2(float x) { return __builtin_amdgcn_exp2f(x); }
; DI void moba_tile(const unsigned char* lds, LAS unsigned char* lds3, const bf16x8 (&qf)[4], int nsub, int diag_sub, int lane, f32x16 (&o)[2], float& m, float& l) {
;     ...
;     for (int kk = 0; kk < nsub; ++kk) {
;         bf16x8 kf[4], vf[4];
; #pragma unroll
;         for (int c = 0; c < 4; ++c) kf[c] = *(const bf16x8*)(lds + MB_K + (32 * kk + r32) * 144 + (16 * c + 8 * hi) * 2);
; #pragma unroll
;         for (int dt = 0; dt < 2; ++dt) { LAS unsigned char* vb = lds3 + MB_V + dt * 16384 + (32 * kk) * 64 + vlane; vf[2 * dt] = vfrag(vb); vf[2 * dt + 1] = vfrag(vb + 1024); }
;         f32x16 s;
; #pragma unroll
;         for (int i = 0; i < 16; ++i) s[i] = 0.f;
; #pragma unroll
;         for (int c = 0; c < 4; ++c) s = mfma32(kf[c], qf[c], s);
;         if (kk == diag_sub) {
;             const int dq = r32 - 4 * hi;
; #pragma unroll
;             for (int i = 0; i < 16; ++i) s[i] = (((i & 3) + 8 * (i >> 2)) > dq) ? -INFINITY : s[i];
;         }
;         float mx = fmaxf(fmaxf(s[0], s[1]), s[2]);
; #pragma unroll
;         for (int i = 3; i < 15; i += 2) mx = fmaxf(fmaxf(mx, s[i]), s[i + 1]);
;         mx = fmaxf(mx, s[15]);
;         mx = fmaxf(mx, xhalf(mx)) * SCL2;
;         const bool trig = mx > m + 8.f;
;         if (__any(trig)) {
;             const float mn = trig ? mx : m, al = fexp2(m - mn); l *= al; m = mn;
; #pragma unroll
;             for (int dt = 0; dt < 2; ++dt)
; #pragma unroll
;                 for (int i = 0; i < 16; ++i) o[dt][i] *= al;
;         }
.LBB0_1378:
	s_waitcnt vmcnt(15) lgkmcnt(0)
	v_mfma_f32_32x32x16_bf16 v[34:49], v[192:195], v[114:117], 0
	v_mfma_f32_32x32x16_bf16 v[34:49], v[196:199], v[110:113], v[34:49]
	v_mfma_f32_32x32x16_bf16 v[34:49], v[200:203], v[106:109], v[34:49]
	v_mfma_f32_32x32x16_bf16 v[34:49], v[204:207], v[102:105], v[34:49]
	v_add_u32_e32 v0, s67, v172
	ds_read_b128 v[192:195], v0 offset:4608
	ds_read_b128 v[196:199], v0 offset:4640
	ds_read_b128 v[200:203], v0 offset:4672
	ds_read_b128 v[204:207], v0 offset:4704
	v_add_u32_e32 v0, s67, v173
	ds_read_b64_tr_b16 v[130:131], v0 offset:36864
	ds_read_b64_tr_b16 v[132:133], v0 offset:37376
	ds_read_b64_tr_b16 v[126:127], v0 offset:37888
	ds_read_b64_tr_b16 v[128:129], v0 offset:38400
	s_nop 2
	v_max_f32_e32 v118, v35, v35
	v_max_f32_e32 v119, v34, v34
	v_max_f32_e32 v118, v119, v118
	v_max3_f32 v118, v118, v36, v37
	v_max3_f32 v118, v118, v38, v39
	v_max3_f32 v118, v118, v40, v41
	v_max3_f32 v118, v118, v42, v43
	v_max3_f32 v118, v118, v44, v45
	v_max3_f32 v118, v118, v46, v47
	v_max3_f32 v174, v118, v48, v49
	v_mov_b32_e32 v175, v174
	ds_read_b64_tr_b16 v[122:123], v0 offset:53248
	ds_read_b64_tr_b16 v[124:125], v0 offset:53760
	ds_read_b64_tr_b16 v[118:119], v0 offset:54272
	ds_read_b64_tr_b16 v[120:121], v0 offset:54784
	s_waitcnt lgkmcnt(4)
	v_permlane32_swap_b32_e32 v174, v175
	v_max_f32_e32 v0, v174, v175
	v_mul_f32_e32 v0, 0x3e38aa3b, v0
	v_add_f32_e32 v174, 0x41000000, v170
	v_cmp_gt_f32_e32 vcc, v0, v174
	s_cbranch_vccz .LBB0_1377
	s_nop 0
	v_cndmask_b32_e32 v174, v170, v0, vcc
	v_sub_f32_e32 v0, v170, v174
	v_exp_f32_e32 v0, v0
	v_mov_b32_e32 v170, v174
	v_mul_f32_e32 v171, v171, v0
	v_pk_mul_f32 v[32:33], v[32:33], v[0:1] op_sel_hi:[1,0]
	v_pk_mul_f32 v[30:31], v[30:31], v[0:1] op_sel_hi:[1,0]
	v_pk_mul_f32 v[28:29], v[28:29], v[0:1] op_sel_hi:[1,0]
	v_pk_mul_f32 v[26:27], v[26:27], v[0:1] op_sel_hi:[1,0]
	v_pk_mul_f32 v[24:25], v[24:25], v[0:1] op_sel_hi:[1,0]
	v_pk_mul_f32 v[22:23], v[22:23], v[0:1] op_sel_hi:[1,0]
	v_pk_mul_f32 v[20:21], v[20:21], v[0:1] op_sel_hi:[1,0]
	v_pk_mul_f32 v[18:19], v[18:19], v[0:1] op_sel_hi:[1,0]
	v_pk_mul_f32 v[16:17], v[16:17], v[0:1] op_sel_hi:[1,0]
	v_pk_mul_f32 v[14:15], v[14:15], v[0:1] op_sel_hi:[1,0]
	v_pk_mul_f32 v[12:13], v[12:13], v[0:1] op_sel_hi:[1,0]
	v_pk_mul_f32 v[10:11], v[10:11], v[0:1] op_sel_hi:[1,0]
	v_pk_mul_f32 v[8:9], v[8:9], v[0:1] op_sel_hi:[1,0]
	v_pk_mul_f32 v[6:7], v[6:7], v[0:1] op_sel_hi:[1,0]
	v_pk_mul_f32 v[4:5], v[4:5], v[0:1] op_sel_hi:[1,0]
	v_pk_mul_f32 v[2:3], v[2:3], v[0:1] op_sel_hi:[1,0]
	s_branch .LBB0_1377
